# vp56 plus loop-edge edit: attention steady-loop bookkeeping (slot rotation, pointer bumps, l_reg adds, exit compare) moved in front of the per-step barriers
# speedup vs baseline: 1.0002x; 1.0002x over previous
.LBB0_311:
	s_mov_b32 s37, s36
	s_mov_b32 s4, s33
	s_mov_b32 s1, s42
	v_add_u32_e32 v209, s5, v252
	ds_read_b64_tr_b16 v[216:217], v209 offset:24576
	ds_read_b64_tr_b16 v[218:219], v209 offset:25088
	v_add_f32_e32 v65, v96, v97
	v_add_f32_e32 v65, v98, v65
	v_add_f32_e32 v65, v99, v65
	v_add_f32_e32 v65, v100, v65
	v_add_f32_e32 v65, v101, v65
	v_cvt_pk_bf16_f32 v172, v96, v97
	v_cvt_pk_bf16_f32 v173, v98, v99
	s_waitcnt lgkmcnt(9)
	v_mfma_f32_32x32x16_bf16 v[128:143], v[204:207], v[156:159], v[230:245]
	ds_read_b64_tr_b16 v[204:205], v209 offset:28672
	ds_read_b64_tr_b16 v[206:207], v209 offset:29184
	v_add_f32_e32 v65, v102, v65
	v_add_f32_e32 v65, v103, v65
	v_add_f32_e32 v65, v104, v65
	v_add_f32_e32 v65, v105, v65
	v_cvt_pk_bf16_f32 v174, v100, v101
	v_cvt_pk_bf16_f32 v175, v102, v103
	s_waitcnt lgkmcnt(10)
	v_mfma_f32_32x32x16_bf16 v[112:127], v[200:203], v[156:159], v[230:245]
	ds_read_b64_tr_b16 v[74:75], v209 offset:25600
	ds_read_b64_tr_b16 v[76:77], v209 offset:26112
	v_add_f32_e32 v65, v106, v65
	v_add_f32_e32 v65, v107, v65
	v_add_f32_e32 v65, v108, v65
	v_add_f32_e32 v65, v109, v65
	v_cvt_pk_bf16_f32 v168, v104, v105
	v_cvt_pk_bf16_f32 v169, v106, v107
	s_waitcnt lgkmcnt(11)
	v_mfma_f32_32x32x16_bf16 v[128:143], v[196:199], v[152:155], v[128:143]
	ds_read_b64_tr_b16 v[70:71], v209 offset:29696
	ds_read_b64_tr_b16 v[72:73], v209 offset:30208
	v_add_f32_e32 v65, v110, v65
	v_add_f32_e32 v65, v111, v65
	v_add_f32_e32 v65, v80, v65
	v_add_f32_e32 v65, v81, v65
	v_cvt_pk_bf16_f32 v170, v108, v109
	v_cvt_pk_bf16_f32 v171, v110, v111
	s_waitcnt lgkmcnt(12)
	v_mfma_f32_32x32x16_bf16 v[112:127], v[192:195], v[152:155], v[112:127]
	ds_read_b64_tr_b16 v[66:67], v209 offset:26624
	ds_read_b64_tr_b16 v[68:69], v209 offset:27136
	v_add_f32_e32 v65, v82, v65
	v_add_f32_e32 v65, v83, v65
	v_add_f32_e32 v65, v84, v65
	v_add_f32_e32 v65, v85, v65
	v_cvt_pk_bf16_f32 v164, v80, v81
	v_cvt_pk_bf16_f32 v165, v82, v83
	s_waitcnt lgkmcnt(13)
	v_mfma_f32_32x32x16_bf16 v[128:143], v[188:191], v[148:151], v[128:143]
	ds_read_b64_tr_b16 v[100:101], v209 offset:30720
	ds_read_b64_tr_b16 v[102:103], v209 offset:31232
	v_add_f32_e32 v65, v86, v65
	v_add_f32_e32 v65, v87, v65
	v_add_f32_e32 v65, v88, v65
	v_add_f32_e32 v65, v89, v65
	v_cvt_pk_bf16_f32 v166, v84, v85
	v_cvt_pk_bf16_f32 v167, v86, v87
	s_waitcnt lgkmcnt(14)
	v_mfma_f32_32x32x16_bf16 v[112:127], v[184:187], v[148:151], v[112:127]
	ds_read_b64_tr_b16 v[96:97], v209 offset:27648
	ds_read_b64_tr_b16 v[98:99], v209 offset:28160
	v_add_f32_e32 v65, v90, v65
	v_add_f32_e32 v65, v91, v65
	v_add_f32_e32 v65, v92, v65
	v_add_f32_e32 v65, v93, v65
	v_cvt_pk_bf16_f32 v160, v88, v89
	v_cvt_pk_bf16_f32 v161, v90, v91
	s_waitcnt lgkmcnt(14)
	v_mfma_f32_32x32x16_bf16 v[128:143], v[180:183], v[144:147], v[128:143]
	ds_read_b64_tr_b16 v[86:87], v209 offset:31744
	ds_read_b64_tr_b16 v[88:89], v209 offset:32256
	v_add_f32_e32 v65, v94, v65
	v_add_f32_e32 v65, v95, v65
	v_add_f32_e32 v65, 0, v65
	v_cvt_pk_bf16_f32 v162, v92, v93
	v_cvt_pk_bf16_f32 v163, v94, v95
	v_mfma_f32_32x32x16_bf16 v[112:127], v[176:179], v[144:147], v[112:127]
	v_lshl_add_u64 v[190:191], v[212:213], 0, s[48:49]
	v_lshl_add_u64 v[78:79], v[190:191], 0, s[10:11]
	s_add_i32 s5, s42, s3
	s_mov_b32 s6, m0
	s_mov_b32 m0, s5
	s_nop 0
	global_load_lds_dwordx4 v[78:79], off
	s_mov_b32 m0, s6
	v_lshl_add_u64 v[188:189], v[210:211], 0, s[48:49]
	v_lshl_add_u64 v[78:79], v[188:189], 0, s[12:13]
	s_add_i32 s5, s36, s97
	s_mov_b32 s6, m0
	s_mov_b32 m0, s5
	s_nop 0
	global_load_lds_dwordx4 v[78:79], off
	s_mov_b32 m0, s6
	v_lshl_add_u64 v[78:79], v[188:189], 0, s[14:15]
	s_add_i32 s5, s36, s96
	s_mov_b32 s6, m0
	s_mov_b32 m0, s5
	s_nop 0
	global_load_lds_dwordx4 v[78:79], off
	s_mov_b32 m0, s6
	s_waitcnt lgkmcnt(14)
	v_mfma_f32_32x32x16_bf16 v[32:47], v[172:175], v[216:219], v[32:47]
	v_exp_f32_e32 v128, v128
	v_exp_f32_e32 v129, v129
	ds_read_b64_tr_b16 v[90:91], v209 offset:49152
	ds_read_b64_tr_b16 v[92:93], v209 offset:49664
	s_waitcnt lgkmcnt(14)
	v_mfma_f32_32x32x16_bf16 v[48:63], v[172:175], v[204:207], v[48:63]
	v_exp_f32_e32 v130, v130
	v_exp_f32_e32 v131, v131
	ds_read_b64_tr_b16 v[104:105], v209 offset:53248
	ds_read_b64_tr_b16 v[106:107], v209 offset:53760
	v_add_u32_e32 v94, s37, v250
	ds_read_b128 v[82:85], v94
	ds_read_b128 v[78:81], v94 offset:512
	s_waitcnt lgkmcnt(14)
	v_mfma_f32_32x32x16_bf16 v[32:47], v[168:171], v[74:77], v[32:47]
	v_exp_f32_e32 v132, v132
	v_exp_f32_e32 v133, v133
	ds_read_b64_tr_b16 v[108:109], v209 offset:50176
	ds_read_b64_tr_b16 v[110:111], v209 offset:50688
	ds_read_b128 v[184:187], v94 offset:2048
	ds_read_b128 v[176:179], v94 offset:2560
	v_mfma_f32_32x32x16_bf16 v[48:63], v[168:171], v[70:73], v[48:63]
	v_exp_f32_e32 v134, v134
	v_exp_f32_e32 v135, v135
	ds_read_b64_tr_b16 v[192:193], v209 offset:54272
	ds_read_b64_tr_b16 v[194:195], v209 offset:54784
	ds_read_b128 v[180:183], v94 offset:4096
	ds_read_b128 v[70:73], v94 offset:4608
	s_waitcnt lgkmcnt(14)
	v_mfma_f32_32x32x16_bf16 v[32:47], v[164:167], v[66:69], v[32:47]
	v_exp_f32_e32 v136, v136
	v_exp_f32_e32 v137, v137
	ds_read_b64_tr_b16 v[196:197], v209 offset:51200
	ds_read_b64_tr_b16 v[198:199], v209 offset:51712
	ds_read_b128 v[74:77], v94 offset:6144
	ds_read_b128 v[66:69], v94 offset:6656
	v_mfma_f32_32x32x16_bf16 v[48:63], v[164:167], v[100:103], v[48:63]
	v_exp_f32_e32 v138, v138
	v_exp_f32_e32 v139, v139
	ds_read_b64_tr_b16 v[100:101], v209 offset:55296
	ds_read_b64_tr_b16 v[102:103], v209 offset:55808
	v_mfma_f32_32x32x16_bf16 v[32:47], v[160:163], v[96:99], v[32:47]
	v_exp_f32_e32 v140, v140
	v_exp_f32_e32 v141, v141
	ds_read_b64_tr_b16 v[94:95], v209 offset:52224
	ds_read_b64_tr_b16 v[96:97], v209 offset:52736
	v_mfma_f32_32x32x16_bf16 v[48:63], v[160:163], v[86:89], v[48:63]
	v_exp_f32_e32 v142, v142
	v_exp_f32_e32 v143, v143
	ds_read_b64_tr_b16 v[86:87], v209 offset:56320
	ds_read_b64_tr_b16 v[88:89], v209 offset:56832
	s_waitcnt lgkmcnt(14)
; #define WAIT_BAR(N) asm volatile("s_waitcnt vmcnt(" #N ") lgkmcnt(0)\n\ts_barrier":::"memory")
;   #define RESC() do{ if(resc){ asm volatile("s_waitcnt lgkmcnt(0)":::"memory"); \
;       _Pragma("unroll") for(int d_=0;d_<2;++d_) _Pragma("unroll") for(int r=0;r<16;++r){const float f_=wsf[crow(r,hi)];o[d_][r]*=f_;o2[d_][r]*=f_;} } }while(0)
;   #define ROT() do{sl_prev=sl_cur;sl_cur=sl_next;sl_next=(sl_next==(NSLOT-1)*SLOTB)?0:sl_next+SLOTB;}while(0)
; template<int THRL> __device__ __forceinline__ void attn_unit(int b,int h,int qb,unsigned char*wsb,char*shm,float kmax,const int CMB,float lam){
;     ...
;   int t=1;
;     ...
;   for(;t+5<NT;t+=2){
;     STEP(pB0,pB1,pA0,pA1,t,true,true,true);     WAIT_BAR(3); RESC(); ROT();
;     STEP(pA0,pA1,pB0,pB1,t+1,true,true,true);   WAIT_BAR(3); RESC(); ROT();
	v_mfma_f32_32x32x16_bf16 v[0:15], v[172:175], v[90:93], v[0:15]
	v_exp_f32_e32 v112, v112
	v_exp_f32_e32 v113, v113
	v_mfma_f32_32x32x16_bf16 v[16:31], v[172:175], v[104:107], v[16:31]
	v_exp_f32_e32 v114, v114
	v_exp_f32_e32 v115, v115
	v_mfma_f32_32x32x16_bf16 v[0:15], v[168:171], v[108:111], v[0:15]
	v_exp_f32_e32 v116, v116
	v_exp_f32_e32 v117, v117
	s_waitcnt lgkmcnt(12)
	v_mfma_f32_32x32x16_bf16 v[16:31], v[168:171], v[192:195], v[16:31]
	v_exp_f32_e32 v118, v118
	v_exp_f32_e32 v119, v119
	s_waitcnt lgkmcnt(8)
	v_mfma_f32_32x32x16_bf16 v[0:15], v[164:167], v[196:199], v[0:15]
	v_exp_f32_e32 v120, v120
	v_exp_f32_e32 v121, v121
	s_waitcnt lgkmcnt(4)
	v_mfma_f32_32x32x16_bf16 v[16:31], v[164:167], v[100:103], v[16:31]
	v_exp_f32_e32 v122, v122
	v_exp_f32_e32 v123, v123
	s_waitcnt lgkmcnt(2)
	v_mfma_f32_32x32x16_bf16 v[0:15], v[160:163], v[94:97], v[0:15]
	v_exp_f32_e32 v124, v124
	v_exp_f32_e32 v125, v125
	s_waitcnt lgkmcnt(0)
	v_mfma_f32_32x32x16_bf16 v[16:31], v[160:163], v[86:89], v[16:31]
	v_exp_f32_e32 v126, v126
	v_exp_f32_e32 v127, v127
	s_add_i32 s5, s36, 0x2000
	s_cmpk_lg_i32 s36, 0x4000
	s_cselect_b32 s42, s5, 0
	s_waitcnt vmcnt(3) lgkmcnt(0)
	s_barrier
	v_add_u32_e32 v209, s1, v252
	ds_read_b64_tr_b16 v[192:193], v209 offset:24576
	ds_read_b64_tr_b16 v[194:195], v209 offset:25088
	v_mfma_f32_32x32x16_bf16 v[96:111], v[82:85], v[156:159], v[230:245]
	v_add_f32_e32 v86, v128, v129
	v_add_f32_e32 v86, v130, v86
	v_add_f32_e32 v86, v131, v86
	v_add_f32_e32 v86, v132, v86
	v_add_f32_e32 v86, v133, v86
	v_cvt_pk_bf16_f32 v172, v128, v129
	v_cvt_pk_bf16_f32 v173, v130, v131
	ds_read_b64_tr_b16 v[196:197], v209 offset:28672
	ds_read_b64_tr_b16 v[198:199], v209 offset:29184
	v_add_f32_e32 v82, v134, v86
	v_add_f32_e32 v82, v135, v82
	v_add_f32_e32 v82, v136, v82
	v_add_f32_e32 v128, v137, v82
	v_mfma_f32_32x32x16_bf16 v[80:95], v[78:81], v[156:159], v[230:245]
	v_cvt_pk_bf16_f32 v174, v132, v133
	v_cvt_pk_bf16_f32 v175, v134, v135
	ds_read_b64_tr_b16 v[216:217], v209 offset:25600
	ds_read_b64_tr_b16 v[218:219], v209 offset:26112
	v_mfma_f32_32x32x16_bf16 v[96:111], v[184:187], v[152:155], v[96:111]
	v_add_f32_e32 v78, v138, v128
	v_add_f32_e32 v78, v139, v78
	v_add_f32_e32 v78, v140, v78
	v_add_f32_e32 v78, v141, v78
	v_cvt_pk_bf16_f32 v168, v136, v137
	v_cvt_pk_bf16_f32 v169, v138, v139
	ds_read_b64_tr_b16 v[136:137], v209 offset:29696
	ds_read_b64_tr_b16 v[138:139], v209 offset:30208
	v_mfma_f32_32x32x16_bf16 v[80:95], v[176:179], v[152:155], v[80:95]
	v_add_f32_e32 v78, v142, v78
	v_add_f32_e32 v78, v143, v78
	v_add_f32_e32 v78, v112, v78
	v_add_f32_e32 v78, v113, v78
	v_cvt_pk_bf16_f32 v170, v140, v141
	v_cvt_pk_bf16_f32 v171, v142, v143
	ds_read_b64_tr_b16 v[132:133], v209 offset:26624
	ds_read_b64_tr_b16 v[134:135], v209 offset:27136
	v_mfma_f32_32x32x16_bf16 v[96:111], v[180:183], v[148:151], v[96:111]
	v_add_f32_e32 v78, v114, v78
	v_add_f32_e32 v78, v115, v78
	v_add_f32_e32 v78, v116, v78
	v_add_f32_e32 v78, v117, v78
	v_cvt_pk_bf16_f32 v164, v112, v113
	v_cvt_pk_bf16_f32 v165, v114, v115
	ds_read_b64_tr_b16 v[128:129], v209 offset:30720
	ds_read_b64_tr_b16 v[130:131], v209 offset:31232
	v_mfma_f32_32x32x16_bf16 v[80:95], v[70:73], v[148:151], v[80:95]
	v_add_f32_e32 v78, v118, v78
	v_add_f32_e32 v78, v119, v78
	v_add_f32_e32 v78, v120, v78
	v_add_f32_e32 v78, v121, v78
	v_cvt_pk_bf16_f32 v166, v116, v117
	v_cvt_pk_bf16_f32 v167, v118, v119
	ds_read_b64_tr_b16 v[112:113], v209 offset:27648
	ds_read_b64_tr_b16 v[114:115], v209 offset:28160
	v_mfma_f32_32x32x16_bf16 v[96:111], v[74:77], v[144:147], v[96:111]
	v_add_f32_e32 v70, v122, v78
	v_add_f32_e32 v70, v123, v70
	v_add_f32_e32 v70, v124, v70
	v_add_f32_e32 v78, v125, v70
	v_cvt_pk_bf16_f32 v160, v120, v121
	v_cvt_pk_bf16_f32 v161, v122, v123
	ds_read_b64_tr_b16 v[70:71], v209 offset:31744
	ds_read_b64_tr_b16 v[72:73], v209 offset:32256
	v_mfma_f32_32x32x16_bf16 v[80:95], v[66:69], v[144:147], v[80:95]
	v_add_f32_e32 v74, v126, v78
	v_add_f32_e32 v74, v127, v74
	v_add_f32_e32 v74, 0, v74
	v_cvt_pk_bf16_f32 v162, v124, v125
	v_cvt_pk_bf16_f32 v163, v126, v127
	v_lshl_add_u64 v[66:67], v[190:191], 0, s[16:17]
	s_add_i32 s1, s36, s3
	s_mov_b32 s5, m0
	s_mov_b32 m0, s1
	s_nop 0
	global_load_lds_dwordx4 v[66:67], off
	s_mov_b32 m0, s5
	v_lshl_add_u64 v[66:67], v[188:189], 0, s[18:19]
	s_add_i32 s1, s42, s97
	s_mov_b32 s5, m0
	s_mov_b32 m0, s1
	s_nop 0
	global_load_lds_dwordx4 v[66:67], off
	s_mov_b32 m0, s5
	v_lshl_add_u64 v[66:67], v[188:189], 0, s[20:21]
	s_add_i32 s1, s42, s96
	s_mov_b32 s5, m0
	s_mov_b32 m0, s1
	s_nop 0
	global_load_lds_dwordx4 v[66:67], off
	s_mov_b32 m0, s5
	s_waitcnt lgkmcnt(14)
; #define WAIT_BAR(N) asm volatile("s_waitcnt vmcnt(" #N ") lgkmcnt(0)\n\ts_barrier":::"memory")
;   #define RESC() do{ if(resc){ asm volatile("s_waitcnt lgkmcnt(0)":::"memory"); \
;       _Pragma("unroll") for(int d_=0;d_<2;++d_) _Pragma("unroll") for(int r=0;r<16;++r){const float f_=wsf[crow(r,hi)];o[d_][r]*=f_;o2[d_][r]*=f_;} } }while(0)
;   #define ROT() do{sl_prev=sl_cur;sl_cur=sl_next;sl_next=(sl_next==(NSLOT-1)*SLOTB)?0:sl_next+SLOTB;}while(0)
; template<int THRL> __device__ __forceinline__ void attn_unit(int b,int h,int qb,unsigned char*wsb,char*shm,float kmax,const int CMB,float lam){
;     ...
;   int t=1;
;     ...
;   for(;t+5<NT;t+=2){
;     STEP(pB0,pB1,pA0,pA1,t,true,true,true);     WAIT_BAR(3); RESC(); ROT();
;     STEP(pA0,pA1,pB0,pB1,t+1,true,true,true);   WAIT_BAR(3); RESC(); ROT();
	v_mfma_f32_32x32x16_bf16 v[32:47], v[172:175], v[192:195], v[32:47]
	v_exp_f32_e32 v96, v96
	v_exp_f32_e32 v97, v97
	ds_read_b64_tr_b16 v[66:67], v209 offset:49152
	ds_read_b64_tr_b16 v[68:69], v209 offset:49664
	s_waitcnt lgkmcnt(14)
	v_mfma_f32_32x32x16_bf16 v[48:63], v[172:175], v[196:199], v[48:63]
	v_exp_f32_e32 v98, v98
	v_exp_f32_e32 v99, v99
	ds_read_b64_tr_b16 v[76:77], v209 offset:53248
	ds_read_b64_tr_b16 v[78:79], v209 offset:53760
	v_add_u32_e32 v75, s42, v250
	ds_read_b128 v[204:207], v75
	ds_read_b128 v[200:203], v75 offset:512
	s_waitcnt lgkmcnt(14)
	v_mfma_f32_32x32x16_bf16 v[32:47], v[168:171], v[216:219], v[32:47]
	v_exp_f32_e32 v100, v100
	v_exp_f32_e32 v101, v101
	ds_read_b64_tr_b16 v[116:117], v209 offset:50176
	ds_read_b64_tr_b16 v[118:119], v209 offset:50688
	ds_read_b128 v[196:199], v75 offset:2048
	ds_read_b128 v[192:195], v75 offset:2560
	v_mfma_f32_32x32x16_bf16 v[48:63], v[168:171], v[136:139], v[48:63]
	v_exp_f32_e32 v102, v102
	v_exp_f32_e32 v103, v103
	ds_read_b64_tr_b16 v[120:121], v209 offset:54272
	ds_read_b64_tr_b16 v[122:123], v209 offset:54784
	ds_read_b128 v[188:191], v75 offset:4096
	ds_read_b128 v[184:187], v75 offset:4608
	s_waitcnt lgkmcnt(14)
	v_mfma_f32_32x32x16_bf16 v[32:47], v[164:167], v[132:135], v[32:47]
	v_exp_f32_e32 v104, v104
	v_exp_f32_e32 v105, v105
	ds_read_b64_tr_b16 v[124:125], v209 offset:51200
	ds_read_b64_tr_b16 v[126:127], v209 offset:51712
	ds_read_b128 v[180:183], v75 offset:6144
	ds_read_b128 v[176:179], v75 offset:6656
	v_mfma_f32_32x32x16_bf16 v[48:63], v[164:167], v[128:131], v[48:63]
	v_exp_f32_e32 v106, v106
	v_exp_f32_e32 v107, v107
	ds_read_b64_tr_b16 v[128:129], v209 offset:55296
	ds_read_b64_tr_b16 v[130:131], v209 offset:55808
	v_mfma_f32_32x32x16_bf16 v[32:47], v[160:163], v[112:115], v[32:47]
	v_exp_f32_e32 v108, v108
	v_exp_f32_e32 v109, v109
	ds_read_b64_tr_b16 v[112:113], v209 offset:52224
	ds_read_b64_tr_b16 v[114:115], v209 offset:52736
	v_mfma_f32_32x32x16_bf16 v[48:63], v[160:163], v[70:73], v[48:63]
	v_exp_f32_e32 v110, v110
	v_exp_f32_e32 v111, v111
	ds_read_b64_tr_b16 v[70:71], v209 offset:56320
	ds_read_b64_tr_b16 v[72:73], v209 offset:56832
	s_waitcnt lgkmcnt(14)
	v_mfma_f32_32x32x16_bf16 v[0:15], v[172:175], v[66:69], v[0:15]
	v_exp_f32_e32 v80, v80
	v_exp_f32_e32 v81, v81
	v_mfma_f32_32x32x16_bf16 v[16:31], v[172:175], v[76:79], v[16:31]
	v_exp_f32_e32 v82, v82
	v_exp_f32_e32 v83, v83
	v_mfma_f32_32x32x16_bf16 v[0:15], v[168:171], v[116:119], v[0:15]
	v_exp_f32_e32 v84, v84
	v_exp_f32_e32 v85, v85
	s_waitcnt lgkmcnt(12)
	v_mfma_f32_32x32x16_bf16 v[16:31], v[168:171], v[120:123], v[16:31]
	v_exp_f32_e32 v86, v86
	v_exp_f32_e32 v87, v87
	s_waitcnt lgkmcnt(8)
	v_mfma_f32_32x32x16_bf16 v[0:15], v[164:167], v[124:127], v[0:15]
	v_exp_f32_e32 v88, v88
	v_exp_f32_e32 v89, v89
	s_waitcnt lgkmcnt(4)
	v_mfma_f32_32x32x16_bf16 v[16:31], v[164:167], v[128:131], v[16:31]
	v_exp_f32_e32 v90, v90
	v_exp_f32_e32 v91, v91
	s_waitcnt lgkmcnt(2)
	v_mfma_f32_32x32x16_bf16 v[0:15], v[160:163], v[112:115], v[0:15]
	v_exp_f32_e32 v92, v92
	v_exp_f32_e32 v93, v93
	s_waitcnt lgkmcnt(0)
	v_mfma_f32_32x32x16_bf16 v[16:31], v[160:163], v[70:73], v[16:31]
	v_exp_f32_e32 v94, v94
	v_exp_f32_e32 v95, v95
	s_add_i32 s1, s42, 0x2000
	s_cmpk_lg_i32 s42, 0x4000
	v_add_f32_e32 v64, v64, v65
	s_mov_b32 s5, s36
	s_cselect_b32 s36, s1, 0
	s_add_i32 s33, s33, 2
	v_lshl_add_u64 v[210:211], v[210:211], 0, s[22:23]
	v_lshl_add_u64 v[212:213], v[212:213], 0, s[22:23]
	s_cmp_ge_u32 s33, s89
	v_add_f32_e32 v64, v64, v74
	s_waitcnt vmcnt(3) lgkmcnt(0)
	s_barrier
	s_cbranch_scc0 .LBB0_311
	ds_read_b32 v230, v246
	ds_read_b32 v231, v246 offset:2048
	ds_read_b32 v232, v246 offset:4096
	ds_read_b32 v233, v246 offset:6144
	ds_read_b32 v234, v246 offset:8192
	ds_read_b32 v235, v246 offset:10240
	ds_read_b32 v236, v246 offset:12288
	ds_read_b32 v237, v246 offset:14336
	ds_read_b32 v238, v246 offset:16384
	ds_read_b32 v239, v246 offset:18432
	ds_read_b32 v240, v246 offset:20480
	ds_read_b32 v241, v246 offset:22528
	ds_read_b32 v242, v246 offset:24576
	ds_read_b32 v243, v246 offset:26624
	ds_read_b32 v244, v246 offset:28672
	ds_read_b32 v245, v246 offset:30720
	ds_read_b32 v246, v246 offset:32768
	s_waitcnt lgkmcnt(0)
	s_nop 0
	s_nop 0
	s_nop 0
	s_nop 0
	s_nop 0
	s_nop 0
	s_nop 0
	s_nop 0
	s_nop 0
	s_nop 0
	s_nop 0
	s_nop 0
	s_add_i32 s6, s4, -3
	s_branch .LBB0_314
